# panel barrier after the MQ GEMM made workgroup-local (memory attention reads only the workgroup's own Q head tile)
# speedup vs baseline: 1.0017x; 1.0017x over previous
.LBB0_1131:
	v_readlane_b32 s0, v253, 27
	v_readlane_b32 s1, v253, 28
	s_and_b64 vcc, exec, s[0:1]
	s_cbranch_vccz .LBB0_1137
	s_xor_b64 s[2:3], s[84:85], -1
	s_mov_b64 s[0:1], -1
	s_and_b64 vcc, exec, s[2:3]
	s_cbranch_vccz .LBB0_1161
	s_waitcnt vmcnt(0)
	v_readlane_b32 s0, v252, 36
	s_add_i32 s2, s18, -1
	s_mul_hi_i32 s3, s2, 0x38e38e39
	s_lshr_b32 s4, s3, 31
	s_ashr_i32 s3, s3, 1
	s_add_i32 s3, s3, s4
	s_mul_i32 s3, s3, 9
	s_sub_i32 s2, s2, s3
	s_cmp_lg_u32 s2, 4
	s_cselect_b32 s2, 1, 0
	s_add_i32 s26, s0, s2
	s_waitcnt vmcnt(0) lgkmcnt(0)
	s_barrier
	s_mov_b64 s[0:1], exec
	v_readlane_b32 s2, v251, 5
	v_readlane_b32 s3, v251, 6
	s_and_b64 s[2:3], s[0:1], s[2:3]
	s_mov_b64 exec, s[2:3]
	s_cbranch_execz .LBB0_1160
	s_add_i32 s2, s18, -1
	s_mul_hi_i32 s3, s2, 0x38e38e39
	s_lshr_b32 s4, s3, 31
	s_ashr_i32 s3, s3, 1
	s_add_i32 s3, s3, s4
	s_mul_i32 s3, s3, 9
	s_sub_i32 s2, s2, s3
	s_cmp_eq_u32 s2, 4
	s_cbranch_scc1 .Lpb_local_inv
	s_cmp_lg_u32 s2, 99
	v_readlane_b32 s4, v252, 43
	s_cselect_b64 s[2:3], -1, 0
	v_readlane_b32 s5, v252, 44
	s_and_b64 s[2:3], s[4:5], s[2:3]
	s_and_b64 vcc, exec, s[2:3]
	s_cbranch_vccnz .LBB0_1136
	buffer_wbl2 sc1
	s_waitcnt vmcnt(0)

.Lpb_local_inv:
	v_readlane_b32 vcc_lo, v252, 43
	v_readlane_b32 vcc_hi, v252, 44
	s_and_b64 vcc, exec, vcc
	s_cbranch_vccz .Lpb_inv_agent
	buffer_inv sc0
	s_branch .Lpb_inv_done
